# sliding-window attention epilogue rewritten (straight-line, 32 all-lane dword stores per lane instead of 64 exec-masked) on top of QK-norm rstd table and diff-attention epilogue rewrite
# baseline (speedup 1.0000x reference)
.LBB0_1045:
	s_or_b64 exec, exec, s[4:5]
	v_mov_b32_e32 v17, v221
	v_mov_b32_e32 v98, v220
	v_lshl_add_u32 v17, v17, 2, s21
	ds_read2_b32 v[96:97], v17 offset1:1
	ds_read2_b32 v[30:31], v17 offset0:2 offset1:3
	ds_read2_b32 v[28:29], v17 offset0:8 offset1:9
	ds_read2_b32 v[26:27], v17 offset0:10 offset1:11
	ds_read2_b32 v[24:25], v17 offset0:16 offset1:17
	ds_read2_b32 v[22:23], v17 offset0:18 offset1:19
	ds_read2_b32 v[20:21], v17 offset0:24 offset1:25
	ds_read2_b32 v[18:19], v17 offset0:26 offset1:27
	s_mov_b32 s21, s80
	s_mul_hi_i32 s5, s21, s2
	s_mul_i32 s4, s21, s2
	s_lshl_b64 s[4:5], s[4:5], 1
	s_add_u32 s4, s50, s4
	s_addc_u32 s5, s51, s5
	s_lshl_b32 s22, s21, 1
	v_and_b32_e32 v99, 1, v219
	v_cmp_eq_u32_e64 s[68:69], 0, v99
	v_mul_lo_u32 v98, v220, s21
	v_lshlrev_b32_e32 v98, 3, v98
	v_lshl_add_u32 v98, v219, 1, v98
	v_mul_u32_u24_e32 v17, 62, v99
	v_add_u32_e32 v98, v98, v17
	s_waitcnt lgkmcnt(0)
	v_rcp_f32_e32 v96, v96
	v_rcp_f32_e32 v97, v97
	v_rcp_f32_e32 v30, v30
	v_rcp_f32_e32 v31, v31
	v_rcp_f32_e32 v28, v28
	v_rcp_f32_e32 v29, v29
	v_rcp_f32_e32 v26, v26
	v_rcp_f32_e32 v27, v27
	v_rcp_f32_e32 v24, v24
	v_rcp_f32_e32 v25, v25
	v_rcp_f32_e32 v22, v22
	v_rcp_f32_e32 v23, v23
	v_rcp_f32_e32 v20, v20
	v_rcp_f32_e32 v21, v21
	v_rcp_f32_e32 v18, v18
	v_rcp_f32_e32 v19, v19
	v_mov_b32_e32 v99, v98
	v_mul_f32_e32 v64, v64, v96
	v_mul_f32_e32 v80, v80, v96
	v_mul_f32_e32 v48, v48, v96
	v_mul_f32_e32 v32, v32, v96
	v_mov_b32_dpp v100, v64 quad_perm:[1,0,3,2] row_mask:0xf bank_mask:0xf bound_ctrl:1
	v_mov_b32_dpp v101, v80 quad_perm:[1,0,3,2] row_mask:0xf bank_mask:0xf bound_ctrl:1
	v_mov_b32_dpp v102, v48 quad_perm:[1,0,3,2] row_mask:0xf bank_mask:0xf bound_ctrl:1
	v_mov_b32_dpp v103, v32 quad_perm:[1,0,3,2] row_mask:0xf bank_mask:0xf bound_ctrl:1
	v_cvt_pk_bf16_f32 v100, v64, v100
	v_cvt_pk_bf16_f32 v101, v101, v80
	v_cndmask_b32_e64 v100, v101, v100, s[68:69]
	global_store_dword v99, v100, s[4:5] offset:0
	v_cvt_pk_bf16_f32 v102, v48, v102
	v_cvt_pk_bf16_f32 v103, v103, v32
	v_cndmask_b32_e64 v102, v103, v102, s[68:69]
	global_store_dword v99, v102, s[4:5] offset:128
	s_mul_i32 s23, s22, 1
	v_add_u32_e32 v99, s23, v98
	v_mul_f32_e32 v65, v65, v97
	v_mul_f32_e32 v81, v81, v97
	v_mul_f32_e32 v49, v49, v97
	v_mul_f32_e32 v33, v33, v97
	v_mov_b32_dpp v100, v65 quad_perm:[1,0,3,2] row_mask:0xf bank_mask:0xf bound_ctrl:1
	v_mov_b32_dpp v101, v81 quad_perm:[1,0,3,2] row_mask:0xf bank_mask:0xf bound_ctrl:1
	v_mov_b32_dpp v102, v49 quad_perm:[1,0,3,2] row_mask:0xf bank_mask:0xf bound_ctrl:1
	v_mov_b32_dpp v103, v33 quad_perm:[1,0,3,2] row_mask:0xf bank_mask:0xf bound_ctrl:1
	v_cvt_pk_bf16_f32 v100, v65, v100
	v_cvt_pk_bf16_f32 v101, v101, v81
	v_cndmask_b32_e64 v100, v101, v100, s[68:69]
	global_store_dword v99, v100, s[4:5] offset:0
	v_cvt_pk_bf16_f32 v102, v49, v102
	v_cvt_pk_bf16_f32 v103, v103, v33
	v_cndmask_b32_e64 v102, v103, v102, s[68:69]
	global_store_dword v99, v102, s[4:5] offset:128
	s_mul_i32 s23, s22, 2
	v_add_u32_e32 v99, s23, v98
	v_mul_f32_e32 v66, v66, v30
	v_mul_f32_e32 v82, v82, v30
	v_mul_f32_e32 v50, v50, v30
	v_mul_f32_e32 v34, v34, v30
	v_mov_b32_dpp v100, v66 quad_perm:[1,0,3,2] row_mask:0xf bank_mask:0xf bound_ctrl:1
	v_mov_b32_dpp v101, v82 quad_perm:[1,0,3,2] row_mask:0xf bank_mask:0xf bound_ctrl:1
	v_mov_b32_dpp v102, v50 quad_perm:[1,0,3,2] row_mask:0xf bank_mask:0xf bound_ctrl:1
	v_mov_b32_dpp v103, v34 quad_perm:[1,0,3,2] row_mask:0xf bank_mask:0xf bound_ctrl:1
	v_cvt_pk_bf16_f32 v100, v66, v100
	v_cvt_pk_bf16_f32 v101, v101, v82
	v_cndmask_b32_e64 v100, v101, v100, s[68:69]
	global_store_dword v99, v100, s[4:5] offset:0
	v_cvt_pk_bf16_f32 v102, v50, v102
	v_cvt_pk_bf16_f32 v103, v103, v34
	v_cndmask_b32_e64 v102, v103, v102, s[68:69]
	global_store_dword v99, v102, s[4:5] offset:128
	s_mul_i32 s23, s22, 3
	v_add_u32_e32 v99, s23, v98
	v_mul_f32_e32 v67, v67, v31
	v_mul_f32_e32 v83, v83, v31
	v_mul_f32_e32 v51, v51, v31
	v_mul_f32_e32 v35, v35, v31
	v_mov_b32_dpp v100, v67 quad_perm:[1,0,3,2] row_mask:0xf bank_mask:0xf bound_ctrl:1
	v_mov_b32_dpp v101, v83 quad_perm:[1,0,3,2] row_mask:0xf bank_mask:0xf bound_ctrl:1
	v_mov_b32_dpp v102, v51 quad_perm:[1,0,3,2] row_mask:0xf bank_mask:0xf bound_ctrl:1
	v_mov_b32_dpp v103, v35 quad_perm:[1,0,3,2] row_mask:0xf bank_mask:0xf bound_ctrl:1
	v_cvt_pk_bf16_f32 v100, v67, v100
	v_cvt_pk_bf16_f32 v101, v101, v83
	v_cndmask_b32_e64 v100, v101, v100, s[68:69]
	global_store_dword v99, v100, s[4:5] offset:0
	v_cvt_pk_bf16_f32 v102, v51, v102
	v_cvt_pk_bf16_f32 v103, v103, v35
	v_cndmask_b32_e64 v102, v103, v102, s[68:69]
	global_store_dword v99, v102, s[4:5] offset:128
	s_mul_i32 s23, s22, 8
	v_add_u32_e32 v99, s23, v98
	v_mul_f32_e32 v68, v68, v28
	v_mul_f32_e32 v84, v84, v28
	v_mul_f32_e32 v52, v52, v28
	v_mul_f32_e32 v36, v36, v28
	v_mov_b32_dpp v100, v68 quad_perm:[1,0,3,2] row_mask:0xf bank_mask:0xf bound_ctrl:1
	v_mov_b32_dpp v101, v84 quad_perm:[1,0,3,2] row_mask:0xf bank_mask:0xf bound_ctrl:1
	v_mov_b32_dpp v102, v52 quad_perm:[1,0,3,2] row_mask:0xf bank_mask:0xf bound_ctrl:1
	v_mov_b32_dpp v103, v36 quad_perm:[1,0,3,2] row_mask:0xf bank_mask:0xf bound_ctrl:1
	v_cvt_pk_bf16_f32 v100, v68, v100
	v_cvt_pk_bf16_f32 v101, v101, v84
	v_cndmask_b32_e64 v100, v101, v100, s[68:69]
	global_store_dword v99, v100, s[4:5] offset:0
	v_cvt_pk_bf16_f32 v102, v52, v102
	v_cvt_pk_bf16_f32 v103, v103, v36
	v_cndmask_b32_e64 v102, v103, v102, s[68:69]
	global_store_dword v99, v102, s[4:5] offset:128
	s_mul_i32 s23, s22, 9
	v_add_u32_e32 v99, s23, v98
	v_mul_f32_e32 v69, v69, v29
	v_mul_f32_e32 v85, v85, v29
	v_mul_f32_e32 v53, v53, v29
	v_mul_f32_e32 v37, v37, v29
	v_mov_b32_dpp v100, v69 quad_perm:[1,0,3,2] row_mask:0xf bank_mask:0xf bound_ctrl:1
	v_mov_b32_dpp v101, v85 quad_perm:[1,0,3,2] row_mask:0xf bank_mask:0xf bound_ctrl:1
	v_mov_b32_dpp v102, v53 quad_perm:[1,0,3,2] row_mask:0xf bank_mask:0xf bound_ctrl:1
	v_mov_b32_dpp v103, v37 quad_perm:[1,0,3,2] row_mask:0xf bank_mask:0xf bound_ctrl:1
	v_cvt_pk_bf16_f32 v100, v69, v100
	v_cvt_pk_bf16_f32 v101, v101, v85
	v_cndmask_b32_e64 v100, v101, v100, s[68:69]
	global_store_dword v99, v100, s[4:5] offset:0
	v_cvt_pk_bf16_f32 v102, v53, v102
	v_cvt_pk_bf16_f32 v103, v103, v37
	v_cndmask_b32_e64 v102, v103, v102, s[68:69]
	global_store_dword v99, v102, s[4:5] offset:128
	s_mul_i32 s23, s22, 10
	v_add_u32_e32 v99, s23, v98
	v_mul_f32_e32 v70, v70, v26
	v_mul_f32_e32 v86, v86, v26
	v_mul_f32_e32 v54, v54, v26
	v_mul_f32_e32 v38, v38, v26
	v_mov_b32_dpp v100, v70 quad_perm:[1,0,3,2] row_mask:0xf bank_mask:0xf bound_ctrl:1
	v_mov_b32_dpp v101, v86 quad_perm:[1,0,3,2] row_mask:0xf bank_mask:0xf bound_ctrl:1
	v_mov_b32_dpp v102, v54 quad_perm:[1,0,3,2] row_mask:0xf bank_mask:0xf bound_ctrl:1
	v_mov_b32_dpp v103, v38 quad_perm:[1,0,3,2] row_mask:0xf bank_mask:0xf bound_ctrl:1
	v_cvt_pk_bf16_f32 v100, v70, v100
	v_cvt_pk_bf16_f32 v101, v101, v86
	v_cndmask_b32_e64 v100, v101, v100, s[68:69]
	global_store_dword v99, v100, s[4:5] offset:0
	v_cvt_pk_bf16_f32 v102, v54, v102
	v_cvt_pk_bf16_f32 v103, v103, v38
	v_cndmask_b32_e64 v102, v103, v102, s[68:69]
	global_store_dword v99, v102, s[4:5] offset:128
	s_mul_i32 s23, s22, 11
	v_add_u32_e32 v99, s23, v98
	v_mul_f32_e32 v71, v71, v27
	v_mul_f32_e32 v87, v87, v27
	v_mul_f32_e32 v55, v55, v27
	v_mul_f32_e32 v39, v39, v27
	v_mov_b32_dpp v100, v71 quad_perm:[1,0,3,2] row_mask:0xf bank_mask:0xf bound_ctrl:1
	v_mov_b32_dpp v101, v87 quad_perm:[1,0,3,2] row_mask:0xf bank_mask:0xf bound_ctrl:1
	v_mov_b32_dpp v102, v55 quad_perm:[1,0,3,2] row_mask:0xf bank_mask:0xf bound_ctrl:1
	v_mov_b32_dpp v103, v39 quad_perm:[1,0,3,2] row_mask:0xf bank_mask:0xf bound_ctrl:1
	v_cvt_pk_bf16_f32 v100, v71, v100
	v_cvt_pk_bf16_f32 v101, v101, v87
	v_cndmask_b32_e64 v100, v101, v100, s[68:69]
	global_store_dword v99, v100, s[4:5] offset:0
	v_cvt_pk_bf16_f32 v102, v55, v102
	v_cvt_pk_bf16_f32 v103, v103, v39
	v_cndmask_b32_e64 v102, v103, v102, s[68:69]
	global_store_dword v99, v102, s[4:5] offset:128
	s_mul_i32 s23, s22, 16
	v_add_u32_e32 v99, s23, v98
	v_mul_f32_e32 v72, v72, v24
	v_mul_f32_e32 v88, v88, v24
	v_mul_f32_e32 v56, v56, v24
	v_mul_f32_e32 v40, v40, v24
	v_mov_b32_dpp v100, v72 quad_perm:[1,0,3,2] row_mask:0xf bank_mask:0xf bound_ctrl:1
	v_mov_b32_dpp v101, v88 quad_perm:[1,0,3,2] row_mask:0xf bank_mask:0xf bound_ctrl:1
	v_mov_b32_dpp v102, v56 quad_perm:[1,0,3,2] row_mask:0xf bank_mask:0xf bound_ctrl:1
	v_mov_b32_dpp v103, v40 quad_perm:[1,0,3,2] row_mask:0xf bank_mask:0xf bound_ctrl:1
	v_cvt_pk_bf16_f32 v100, v72, v100
	v_cvt_pk_bf16_f32 v101, v101, v88
	v_cndmask_b32_e64 v100, v101, v100, s[68:69]
	global_store_dword v99, v100, s[4:5] offset:0
	v_cvt_pk_bf16_f32 v102, v56, v102
	v_cvt_pk_bf16_f32 v103, v103, v40
	v_cndmask_b32_e64 v102, v103, v102, s[68:69]
	global_store_dword v99, v102, s[4:5] offset:128
	s_mul_i32 s23, s22, 17
	v_add_u32_e32 v99, s23, v98
	v_mul_f32_e32 v73, v73, v25
	v_mul_f32_e32 v89, v89, v25
	v_mul_f32_e32 v57, v57, v25
	v_mul_f32_e32 v41, v41, v25
	v_mov_b32_dpp v100, v73 quad_perm:[1,0,3,2] row_mask:0xf bank_mask:0xf bound_ctrl:1
	v_mov_b32_dpp v101, v89 quad_perm:[1,0,3,2] row_mask:0xf bank_mask:0xf bound_ctrl:1
	v_mov_b32_dpp v102, v57 quad_perm:[1,0,3,2] row_mask:0xf bank_mask:0xf bound_ctrl:1
	v_mov_b32_dpp v103, v41 quad_perm:[1,0,3,2] row_mask:0xf bank_mask:0xf bound_ctrl:1
	v_cvt_pk_bf16_f32 v100, v73, v100
	v_cvt_pk_bf16_f32 v101, v101, v89
	v_cndmask_b32_e64 v100, v101, v100, s[68:69]
	global_store_dword v99, v100, s[4:5] offset:0
	v_cvt_pk_bf16_f32 v102, v57, v102
	v_cvt_pk_bf16_f32 v103, v103, v41
	v_cndmask_b32_e64 v102, v103, v102, s[68:69]
	global_store_dword v99, v102, s[4:5] offset:128
	s_mul_i32 s23, s22, 18
	v_add_u32_e32 v99, s23, v98
	v_mul_f32_e32 v74, v74, v22
	v_mul_f32_e32 v90, v90, v22
	v_mul_f32_e32 v58, v58, v22
	v_mul_f32_e32 v42, v42, v22
	v_mov_b32_dpp v100, v74 quad_perm:[1,0,3,2] row_mask:0xf bank_mask:0xf bound_ctrl:1
	v_mov_b32_dpp v101, v90 quad_perm:[1,0,3,2] row_mask:0xf bank_mask:0xf bound_ctrl:1
	v_mov_b32_dpp v102, v58 quad_perm:[1,0,3,2] row_mask:0xf bank_mask:0xf bound_ctrl:1
	v_mov_b32_dpp v103, v42 quad_perm:[1,0,3,2] row_mask:0xf bank_mask:0xf bound_ctrl:1
	v_cvt_pk_bf16_f32 v100, v74, v100
	v_cvt_pk_bf16_f32 v101, v101, v90
	v_cndmask_b32_e64 v100, v101, v100, s[68:69]
	global_store_dword v99, v100, s[4:5] offset:0
	v_cvt_pk_bf16_f32 v102, v58, v102
	v_cvt_pk_bf16_f32 v103, v103, v42
	v_cndmask_b32_e64 v102, v103, v102, s[68:69]
	global_store_dword v99, v102, s[4:5] offset:128
	s_mul_i32 s23, s22, 19
	v_add_u32_e32 v99, s23, v98
	v_mul_f32_e32 v75, v75, v23
	v_mul_f32_e32 v91, v91, v23
	v_mul_f32_e32 v59, v59, v23
	v_mul_f32_e32 v43, v43, v23
	v_mov_b32_dpp v100, v75 quad_perm:[1,0,3,2] row_mask:0xf bank_mask:0xf bound_ctrl:1
	v_mov_b32_dpp v101, v91 quad_perm:[1,0,3,2] row_mask:0xf bank_mask:0xf bound_ctrl:1
	v_mov_b32_dpp v102, v59 quad_perm:[1,0,3,2] row_mask:0xf bank_mask:0xf bound_ctrl:1
	v_mov_b32_dpp v103, v43 quad_perm:[1,0,3,2] row_mask:0xf bank_mask:0xf bound_ctrl:1
	v_cvt_pk_bf16_f32 v100, v75, v100
	v_cvt_pk_bf16_f32 v101, v101, v91
	v_cndmask_b32_e64 v100, v101, v100, s[68:69]
	global_store_dword v99, v100, s[4:5] offset:0
	v_cvt_pk_bf16_f32 v102, v59, v102
	v_cvt_pk_bf16_f32 v103, v103, v43
	v_cndmask_b32_e64 v102, v103, v102, s[68:69]
	global_store_dword v99, v102, s[4:5] offset:128
	s_mul_i32 s23, s22, 24
	v_add_u32_e32 v99, s23, v98
	v_mul_f32_e32 v76, v76, v20
	v_mul_f32_e32 v92, v92, v20
	v_mul_f32_e32 v60, v60, v20
	v_mul_f32_e32 v44, v44, v20
	v_mov_b32_dpp v100, v76 quad_perm:[1,0,3,2] row_mask:0xf bank_mask:0xf bound_ctrl:1
	v_mov_b32_dpp v101, v92 quad_perm:[1,0,3,2] row_mask:0xf bank_mask:0xf bound_ctrl:1
	v_mov_b32_dpp v102, v60 quad_perm:[1,0,3,2] row_mask:0xf bank_mask:0xf bound_ctrl:1
	v_mov_b32_dpp v103, v44 quad_perm:[1,0,3,2] row_mask:0xf bank_mask:0xf bound_ctrl:1
	v_cvt_pk_bf16_f32 v100, v76, v100
	v_cvt_pk_bf16_f32 v101, v101, v92
	v_cndmask_b32_e64 v100, v101, v100, s[68:69]
	global_store_dword v99, v100, s[4:5] offset:0
	v_cvt_pk_bf16_f32 v102, v60, v102
	v_cvt_pk_bf16_f32 v103, v103, v44
	v_cndmask_b32_e64 v102, v103, v102, s[68:69]
	global_store_dword v99, v102, s[4:5] offset:128
	s_mul_i32 s23, s22, 25
	v_add_u32_e32 v99, s23, v98
	v_mul_f32_e32 v77, v77, v21
	v_mul_f32_e32 v93, v93, v21
	v_mul_f32_e32 v61, v61, v21
	v_mul_f32_e32 v45, v45, v21
	v_mov_b32_dpp v100, v77 quad_perm:[1,0,3,2] row_mask:0xf bank_mask:0xf bound_ctrl:1
	v_mov_b32_dpp v101, v93 quad_perm:[1,0,3,2] row_mask:0xf bank_mask:0xf bound_ctrl:1
	v_mov_b32_dpp v102, v61 quad_perm:[1,0,3,2] row_mask:0xf bank_mask:0xf bound_ctrl:1
	v_mov_b32_dpp v103, v45 quad_perm:[1,0,3,2] row_mask:0xf bank_mask:0xf bound_ctrl:1
	v_cvt_pk_bf16_f32 v100, v77, v100
	v_cvt_pk_bf16_f32 v101, v101, v93
	v_cndmask_b32_e64 v100, v101, v100, s[68:69]
	global_store_dword v99, v100, s[4:5] offset:0
	v_cvt_pk_bf16_f32 v102, v61, v102
	v_cvt_pk_bf16_f32 v103, v103, v45
	v_cndmask_b32_e64 v102, v103, v102, s[68:69]
	global_store_dword v99, v102, s[4:5] offset:128
	s_mul_i32 s23, s22, 26
	v_add_u32_e32 v99, s23, v98
	v_mul_f32_e32 v78, v78, v18
	v_mul_f32_e32 v94, v94, v18
	v_mul_f32_e32 v62, v62, v18
	v_mul_f32_e32 v46, v46, v18
	v_mov_b32_dpp v100, v78 quad_perm:[1,0,3,2] row_mask:0xf bank_mask:0xf bound_ctrl:1
	v_mov_b32_dpp v101, v94 quad_perm:[1,0,3,2] row_mask:0xf bank_mask:0xf bound_ctrl:1
	v_mov_b32_dpp v102, v62 quad_perm:[1,0,3,2] row_mask:0xf bank_mask:0xf bound_ctrl:1
	v_mov_b32_dpp v103, v46 quad_perm:[1,0,3,2] row_mask:0xf bank_mask:0xf bound_ctrl:1
	v_cvt_pk_bf16_f32 v100, v78, v100
	v_cvt_pk_bf16_f32 v101, v101, v94
	v_cndmask_b32_e64 v100, v101, v100, s[68:69]
	global_store_dword v99, v100, s[4:5] offset:0
	v_cvt_pk_bf16_f32 v102, v62, v102
	v_cvt_pk_bf16_f32 v103, v103, v46
	v_cndmask_b32_e64 v102, v103, v102, s[68:69]
	global_store_dword v99, v102, s[4:5] offset:128
	s_mul_i32 s23, s22, 27
	v_add_u32_e32 v99, s23, v98
	v_mul_f32_e32 v79, v79, v19
	v_mul_f32_e32 v95, v95, v19
	v_mul_f32_e32 v63, v63, v19
	v_mul_f32_e32 v47, v47, v19
	v_mov_b32_dpp v100, v79 quad_perm:[1,0,3,2] row_mask:0xf bank_mask:0xf bound_ctrl:1
	v_mov_b32_dpp v101, v95 quad_perm:[1,0,3,2] row_mask:0xf bank_mask:0xf bound_ctrl:1
	v_mov_b32_dpp v102, v63 quad_perm:[1,0,3,2] row_mask:0xf bank_mask:0xf bound_ctrl:1
	v_mov_b32_dpp v103, v47 quad_perm:[1,0,3,2] row_mask:0xf bank_mask:0xf bound_ctrl:1
	v_cvt_pk_bf16_f32 v100, v79, v100
	v_cvt_pk_bf16_f32 v101, v101, v95
	v_cndmask_b32_e64 v100, v101, v100, s[68:69]
	global_store_dword v99, v100, s[4:5] offset:0
	v_cvt_pk_bf16_f32 v102, v63, v102
	v_cvt_pk_bf16_f32 v103, v103, v47
	v_cndmask_b32_e64 v102, v103, v102, s[68:69]
	global_store_dword v99, v102, s[4:5] offset:128
